# instruction selection: v_mul_u32_u24 instead of quarter-rate v_mul_lo_u32 in rewritten epilogues; packed scaling in attention epilogues
# baseline (speedup 1.0000x reference)
; template <bool FOX> ...
;     ...
;   for (int qt = 0; qt < 2; ++qt) {
;     float lt = xsum32(lrun[qt]);
;     float inv = 1.f / lt;
;     u16* yp = Yb + (size_t)(q0 + qt * 32 + ln) * ldy;
; #pragma unroll
;     for (int dt = 0; dt < 2; ++dt)
; #pragma unroll
;       for (int jj = 0; jj < 4; ++jj) {
;         uint2 pk;
;         pk.x = pack2(o[dt][qt][4 * jj + 0] * inv, o[dt][qt][4 * jj + 1] * inv);
;         pk.y = pack2(o[dt][qt][4 * jj + 2] * inv, o[dt][qt][4 * jj + 3] * inv);
;         *reinterpret_cast<uint2*>(yp + dt * 32 + 8 * jj + 4 * hh) = pk;
;       }
;   }
.LBB0_496:
	s_lshl_b64 s[0:1], s[4:5], 23
	s_add_u32 s0, s30, s0
	s_addc_u32 s1, s31, s1
	s_lshl_b32 s4, s9, 1
	s_add_u32 s0, s0, s4
	s_addc_u32 s1, s1, 0
	v_mov_b32_e32 v66, v64
	v_mov_b32_e32 v67, v164
	v_ashrrev_i32_e32 v169, 31, v168
	s_nop 0
	v_permlane32_swap_b32_e32 v64, v66
	v_permlane32_swap_b32_e32 v164, v67
	v_add_f32_e32 v66, v64, v66
	v_add_f32_e32 v67, v164, v67
	v_lshl_add_u64 v[64:65], v[168:169], 1, s[0:1]
	v_div_scale_f32 v80, s[4:5], v66, v66, 1.0
	v_rcp_f32_e32 v81, v80
	v_div_scale_f32 v82, vcc, 1.0, v66, 1.0
	v_fma_f32 v83, -v80, v81, 1.0
	v_fmac_f32_e32 v81, v83, v81
	v_mul_f32_e32 v83, v82, v81
	v_fma_f32 v84, -v80, v83, v82
	v_fmac_f32_e32 v83, v84, v81
	v_fma_f32 v80, -v80, v83, v82
	v_div_fmas_f32 v80, v80, v81, v83
	v_div_fixup_f32 v68, v80, v66, 1.0
	v_div_scale_f32 v86, s[4:5], v67, v67, 1.0
	v_rcp_f32_e32 v87, v86
	v_div_scale_f32 v88, vcc, 1.0, v67, 1.0
	v_fma_f32 v89, -v86, v87, 1.0
	v_fmac_f32_e32 v87, v89, v87
	v_mul_f32_e32 v89, v88, v87
	v_fma_f32 v90, -v86, v89, v88
	v_fmac_f32_e32 v89, v90, v87
	v_fma_f32 v86, -v86, v89, v88
	v_div_fmas_f32 v86, v86, v87, v89
	v_div_fixup_f32 v70, v86, v67, 1.0
	v_mbcnt_lo_u32_b32 v74, -1, 0
	v_mbcnt_hi_u32_b32 v74, -1, v74
	v_and_b32_e32 v74, 32, v74
	v_lshrrev_b32_e32 v74, 2, v74
	v_mov_b32_e32 v75, 0
	v_lshlrev_b64 v[76:77], 11, v[166:167]
	v_lshlrev_b64 v[78:79], 11, v[162:163]
	v_lshl_add_u64 v[76:77], v[64:65], 0, v[76:77]
	v_lshl_add_u64 v[78:79], v[64:65], 0, v[78:79]
	v_lshl_add_u64 v[76:77], v[76:77], 0, v[74:75]
	v_lshl_add_u64 v[78:79], v[78:79], 0, v[74:75]
	v_pk_mul_f32 v[48:49], v[48:49], v[68:69] op_sel_hi:[1,0]
	v_pk_mul_f32 v[50:51], v[50:51], v[68:69] op_sel_hi:[1,0]
	v_pk_mul_f32 v[52:53], v[52:53], v[68:69] op_sel_hi:[1,0]
	v_pk_mul_f32 v[54:55], v[54:55], v[68:69] op_sel_hi:[1,0]
	v_cvt_pk_bf16_f32 v48, v48, v49
	v_cvt_pk_bf16_f32 v49, v50, v51
	v_cvt_pk_bf16_f32 v50, v52, v53
	v_cvt_pk_bf16_f32 v51, v54, v55
	s_nop 1
	v_permlane32_swap_b32_e32 v48, v50
	v_permlane32_swap_b32_e32 v49, v51
	global_store_dwordx4 v[76:77], v[48:51], off
	v_pk_mul_f32 v[56:57], v[56:57], v[68:69] op_sel_hi:[1,0]
	v_pk_mul_f32 v[58:59], v[58:59], v[68:69] op_sel_hi:[1,0]
	v_pk_mul_f32 v[60:61], v[60:61], v[68:69] op_sel_hi:[1,0]
	v_pk_mul_f32 v[62:63], v[62:63], v[68:69] op_sel_hi:[1,0]
	v_cvt_pk_bf16_f32 v56, v56, v57
	v_cvt_pk_bf16_f32 v57, v58, v59
	v_cvt_pk_bf16_f32 v58, v60, v61
	v_cvt_pk_bf16_f32 v59, v62, v63
	s_nop 1
	v_permlane32_swap_b32_e32 v56, v58
	v_permlane32_swap_b32_e32 v57, v59
	global_store_dwordx4 v[76:77], v[56:59], off offset:32
	v_pk_mul_f32 v[32:33], v[32:33], v[68:69] op_sel_hi:[1,0]
	v_pk_mul_f32 v[34:35], v[34:35], v[68:69] op_sel_hi:[1,0]
	v_pk_mul_f32 v[36:37], v[36:37], v[68:69] op_sel_hi:[1,0]
	v_pk_mul_f32 v[38:39], v[38:39], v[68:69] op_sel_hi:[1,0]
	v_cvt_pk_bf16_f32 v32, v32, v33
	v_cvt_pk_bf16_f32 v33, v34, v35
	v_cvt_pk_bf16_f32 v34, v36, v37
	v_cvt_pk_bf16_f32 v35, v38, v39
	s_nop 1
	v_permlane32_swap_b32_e32 v32, v34
	v_permlane32_swap_b32_e32 v33, v35
	global_store_dwordx4 v[76:77], v[32:35], off offset:64
	v_pk_mul_f32 v[40:41], v[40:41], v[68:69] op_sel_hi:[1,0]
	v_pk_mul_f32 v[42:43], v[42:43], v[68:69] op_sel_hi:[1,0]
	v_pk_mul_f32 v[44:45], v[44:45], v[68:69] op_sel_hi:[1,0]
	v_pk_mul_f32 v[46:47], v[46:47], v[68:69] op_sel_hi:[1,0]
	v_cvt_pk_bf16_f32 v40, v40, v41
	v_cvt_pk_bf16_f32 v41, v42, v43
	v_cvt_pk_bf16_f32 v42, v44, v45
	v_cvt_pk_bf16_f32 v43, v46, v47
	s_nop 1
	v_permlane32_swap_b32_e32 v40, v42
	v_permlane32_swap_b32_e32 v41, v43
	global_store_dwordx4 v[76:77], v[40:43], off offset:96
	v_pk_mul_f32 v[16:17], v[16:17], v[70:71] op_sel_hi:[1,0]
	v_pk_mul_f32 v[18:19], v[18:19], v[70:71] op_sel_hi:[1,0]
	v_pk_mul_f32 v[20:21], v[20:21], v[70:71] op_sel_hi:[1,0]
	v_pk_mul_f32 v[22:23], v[22:23], v[70:71] op_sel_hi:[1,0]
	v_cvt_pk_bf16_f32 v16, v16, v17
	v_cvt_pk_bf16_f32 v17, v18, v19
	v_cvt_pk_bf16_f32 v18, v20, v21
	v_cvt_pk_bf16_f32 v19, v22, v23
	s_nop 1
	v_permlane32_swap_b32_e32 v16, v18
	v_permlane32_swap_b32_e32 v17, v19
	global_store_dwordx4 v[78:79], v[16:19], off
	v_pk_mul_f32 v[24:25], v[24:25], v[70:71] op_sel_hi:[1,0]
	v_pk_mul_f32 v[26:27], v[26:27], v[70:71] op_sel_hi:[1,0]
	v_pk_mul_f32 v[28:29], v[28:29], v[70:71] op_sel_hi:[1,0]
	v_pk_mul_f32 v[30:31], v[30:31], v[70:71] op_sel_hi:[1,0]
	v_cvt_pk_bf16_f32 v24, v24, v25
	v_cvt_pk_bf16_f32 v25, v26, v27
	v_cvt_pk_bf16_f32 v26, v28, v29
	v_cvt_pk_bf16_f32 v27, v30, v31
	s_nop 1
	v_permlane32_swap_b32_e32 v24, v26
	v_permlane32_swap_b32_e32 v25, v27
	global_store_dwordx4 v[78:79], v[24:27], off offset:32
	v_pk_mul_f32 v[0:1], v[0:1], v[70:71] op_sel_hi:[1,0]
	v_pk_mul_f32 v[2:3], v[2:3], v[70:71] op_sel_hi:[1,0]
	v_pk_mul_f32 v[4:5], v[4:5], v[70:71] op_sel_hi:[1,0]
	v_pk_mul_f32 v[6:7], v[6:7], v[70:71] op_sel_hi:[1,0]
	v_cvt_pk_bf16_f32 v0, v0, v1
	v_cvt_pk_bf16_f32 v1, v2, v3
	v_cvt_pk_bf16_f32 v2, v4, v5
	v_cvt_pk_bf16_f32 v3, v6, v7
	s_nop 1
	v_permlane32_swap_b32_e32 v0, v2
	v_permlane32_swap_b32_e32 v1, v3
	global_store_dwordx4 v[78:79], v[0:3], off offset:64
	v_pk_mul_f32 v[8:9], v[8:9], v[70:71] op_sel_hi:[1,0]
	v_pk_mul_f32 v[10:11], v[10:11], v[70:71] op_sel_hi:[1,0]
	v_pk_mul_f32 v[12:13], v[12:13], v[70:71] op_sel_hi:[1,0]
	v_pk_mul_f32 v[14:15], v[14:15], v[70:71] op_sel_hi:[1,0]
	v_cvt_pk_bf16_f32 v8, v8, v9
	v_cvt_pk_bf16_f32 v9, v10, v11
	v_cvt_pk_bf16_f32 v10, v12, v13
	v_cvt_pk_bf16_f32 v11, v14, v15
	s_nop 1
	v_permlane32_swap_b32_e32 v8, v10
	v_permlane32_swap_b32_e32 v9, v11
	global_store_dwordx4 v[78:79], v[8:11], off offset:96
	v_readlane_b32 s0, v251, 20
	s_add_i32 s8, s8, s78
	s_add_i32 s2, s2, s0
	s_cmpk_gt_i32 s8, 0x1ff
	v_readlane_b32 s1, v251, 21
	s_cbranch_scc1 .LBB0_451

; template <bool FOX> ...
;     ...
;   for (int qt = 0; qt < 2; ++qt) {
;     float lt = xsum32(lrun[qt]);
;     float inv = 1.f / lt;
;     u16* yp = Yb + (size_t)(q0 + qt * 32 + ln) * ldy;
; #pragma unroll
;     for (int dt = 0; dt < 2; ++dt)
; #pragma unroll
;       for (int jj = 0; jj < 4; ++jj) {
;         uint2 pk;
;         pk.x = pack2(o[dt][qt][4 * jj + 0] * inv, o[dt][qt][4 * jj + 1] * inv);
;         pk.y = pack2(o[dt][qt][4 * jj + 2] * inv, o[dt][qt][4 * jj + 3] * inv);
;         *reinterpret_cast<uint2*>(yp + dt * 32 + 8 * jj + 4 * hh) = pk;
;       }
;   }
.LBB0_505:
	s_lshl_b32 s5, s5, 10
	s_sub_u32 s5, 0, s5
	s_subb_u32 s7, 0, 0
	s_add_u32 s2, s2, s5
	s_addc_u32 s5, s4, s7
	s_lshl_b32 s4, s6, 1
	s_add_u32 s4, s2, s4
	s_addc_u32 s5, s5, 0
	v_mov_b32_e32 v66, v188
	v_mov_b32_e32 v67, v189
	s_nop 1
	v_permlane32_swap_b32_e32 v188, v66
	v_permlane32_swap_b32_e32 v189, v67
	v_lshl_add_u64 v[64:65], v[186:187], 1, s[4:5]
	s_mov_b64 s[4:5], 0xe840400
	v_add_f32_e32 v66, v188, v66
	v_add_f32_e32 v67, v189, v67
	v_lshl_add_u64 v[64:65], v[64:65], 0, s[4:5]
	v_div_scale_f32 v80, s[4:5], v66, v66, 1.0
	v_rcp_f32_e32 v81, v80
	v_div_scale_f32 v82, vcc, 1.0, v66, 1.0
	v_fma_f32 v83, -v80, v81, 1.0
	v_fmac_f32_e32 v81, v83, v81
	v_mul_f32_e32 v83, v82, v81
	v_fma_f32 v84, -v80, v83, v82
	v_fmac_f32_e32 v83, v84, v81
	v_fma_f32 v80, -v80, v83, v82
	v_div_fmas_f32 v80, v80, v81, v83
	v_div_fixup_f32 v68, v80, v66, 1.0
	v_div_scale_f32 v86, s[4:5], v67, v67, 1.0
	v_rcp_f32_e32 v87, v86
	v_div_scale_f32 v88, vcc, 1.0, v67, 1.0
	v_fma_f32 v89, -v86, v87, 1.0
	v_fmac_f32_e32 v87, v89, v87
	v_mul_f32_e32 v89, v88, v87
	v_fma_f32 v90, -v86, v89, v88
	v_fmac_f32_e32 v89, v90, v87
	v_fma_f32 v86, -v86, v89, v88
	v_div_fmas_f32 v86, v86, v87, v89
	v_div_fixup_f32 v70, v86, v67, 1.0
	v_mbcnt_lo_u32_b32 v74, -1, 0
	v_mbcnt_hi_u32_b32 v74, -1, v74
	v_and_b32_e32 v74, 32, v74
	v_lshrrev_b32_e32 v74, 2, v74
	v_mov_b32_e32 v75, 0
	v_lshlrev_b64 v[76:77], 11, v[180:181]
	v_lshlrev_b64 v[78:79], 11, v[178:179]
	v_lshl_add_u64 v[76:77], v[64:65], 0, v[76:77]
	v_lshl_add_u64 v[78:79], v[64:65], 0, v[78:79]
	v_lshl_add_u64 v[76:77], v[76:77], 0, v[74:75]
	v_lshl_add_u64 v[78:79], v[78:79], 0, v[74:75]
	v_pk_mul_f32 v[48:49], v[48:49], v[68:69] op_sel_hi:[1,0]
	v_pk_mul_f32 v[50:51], v[50:51], v[68:69] op_sel_hi:[1,0]
	v_pk_mul_f32 v[52:53], v[52:53], v[68:69] op_sel_hi:[1,0]
	v_pk_mul_f32 v[54:55], v[54:55], v[68:69] op_sel_hi:[1,0]
	v_cvt_pk_bf16_f32 v48, v48, v49
	v_cvt_pk_bf16_f32 v49, v50, v51
	v_cvt_pk_bf16_f32 v50, v52, v53
	v_cvt_pk_bf16_f32 v51, v54, v55
	s_nop 1
	v_permlane32_swap_b32_e32 v48, v50
	v_permlane32_swap_b32_e32 v49, v51
	global_store_dwordx4 v[76:77], v[48:51], off
	v_pk_mul_f32 v[56:57], v[56:57], v[68:69] op_sel_hi:[1,0]
	v_pk_mul_f32 v[58:59], v[58:59], v[68:69] op_sel_hi:[1,0]
	v_pk_mul_f32 v[60:61], v[60:61], v[68:69] op_sel_hi:[1,0]
	v_pk_mul_f32 v[62:63], v[62:63], v[68:69] op_sel_hi:[1,0]
	v_cvt_pk_bf16_f32 v56, v56, v57
	v_cvt_pk_bf16_f32 v57, v58, v59
	v_cvt_pk_bf16_f32 v58, v60, v61
	v_cvt_pk_bf16_f32 v59, v62, v63
	s_nop 1
	v_permlane32_swap_b32_e32 v56, v58
	v_permlane32_swap_b32_e32 v57, v59
	global_store_dwordx4 v[76:77], v[56:59], off offset:32
	v_pk_mul_f32 v[32:33], v[32:33], v[68:69] op_sel_hi:[1,0]
	v_pk_mul_f32 v[34:35], v[34:35], v[68:69] op_sel_hi:[1,0]
	v_pk_mul_f32 v[36:37], v[36:37], v[68:69] op_sel_hi:[1,0]
	v_pk_mul_f32 v[38:39], v[38:39], v[68:69] op_sel_hi:[1,0]
	v_cvt_pk_bf16_f32 v32, v32, v33
	v_cvt_pk_bf16_f32 v33, v34, v35
	v_cvt_pk_bf16_f32 v34, v36, v37
	v_cvt_pk_bf16_f32 v35, v38, v39
	s_nop 1
	v_permlane32_swap_b32_e32 v32, v34
	v_permlane32_swap_b32_e32 v33, v35
	global_store_dwordx4 v[76:77], v[32:35], off offset:64
	v_pk_mul_f32 v[40:41], v[40:41], v[68:69] op_sel_hi:[1,0]
	v_pk_mul_f32 v[42:43], v[42:43], v[68:69] op_sel_hi:[1,0]
	v_pk_mul_f32 v[44:45], v[44:45], v[68:69] op_sel_hi:[1,0]
	v_pk_mul_f32 v[46:47], v[46:47], v[68:69] op_sel_hi:[1,0]
	v_cvt_pk_bf16_f32 v40, v40, v41
	v_cvt_pk_bf16_f32 v41, v42, v43
	v_cvt_pk_bf16_f32 v42, v44, v45
	v_cvt_pk_bf16_f32 v43, v46, v47
	s_nop 1
	v_permlane32_swap_b32_e32 v40, v42
	v_permlane32_swap_b32_e32 v41, v43
	global_store_dwordx4 v[76:77], v[40:43], off offset:96
	v_pk_mul_f32 v[16:17], v[16:17], v[70:71] op_sel_hi:[1,0]
	v_pk_mul_f32 v[18:19], v[18:19], v[70:71] op_sel_hi:[1,0]
	v_pk_mul_f32 v[20:21], v[20:21], v[70:71] op_sel_hi:[1,0]
	v_pk_mul_f32 v[22:23], v[22:23], v[70:71] op_sel_hi:[1,0]
	v_cvt_pk_bf16_f32 v16, v16, v17
	v_cvt_pk_bf16_f32 v17, v18, v19
	v_cvt_pk_bf16_f32 v18, v20, v21
	v_cvt_pk_bf16_f32 v19, v22, v23
	s_nop 1
	v_permlane32_swap_b32_e32 v16, v18
	v_permlane32_swap_b32_e32 v17, v19
	global_store_dwordx4 v[78:79], v[16:19], off
	v_pk_mul_f32 v[24:25], v[24:25], v[70:71] op_sel_hi:[1,0]
	v_pk_mul_f32 v[26:27], v[26:27], v[70:71] op_sel_hi:[1,0]
	v_pk_mul_f32 v[28:29], v[28:29], v[70:71] op_sel_hi:[1,0]
	v_pk_mul_f32 v[30:31], v[30:31], v[70:71] op_sel_hi:[1,0]
	v_cvt_pk_bf16_f32 v24, v24, v25
	v_cvt_pk_bf16_f32 v25, v26, v27
	v_cvt_pk_bf16_f32 v26, v28, v29
	v_cvt_pk_bf16_f32 v27, v30, v31
	s_nop 1
	v_permlane32_swap_b32_e32 v24, v26
	v_permlane32_swap_b32_e32 v25, v27
	global_store_dwordx4 v[78:79], v[24:27], off offset:32
	v_pk_mul_f32 v[0:1], v[0:1], v[70:71] op_sel_hi:[1,0]
	v_pk_mul_f32 v[2:3], v[2:3], v[70:71] op_sel_hi:[1,0]
	v_pk_mul_f32 v[4:5], v[4:5], v[70:71] op_sel_hi:[1,0]
	v_pk_mul_f32 v[6:7], v[6:7], v[70:71] op_sel_hi:[1,0]
	v_cvt_pk_bf16_f32 v0, v0, v1
	v_cvt_pk_bf16_f32 v1, v2, v3
	v_cvt_pk_bf16_f32 v2, v4, v5
	v_cvt_pk_bf16_f32 v3, v6, v7
	s_nop 1
	v_permlane32_swap_b32_e32 v0, v2
	v_permlane32_swap_b32_e32 v1, v3
	global_store_dwordx4 v[78:79], v[0:3], off offset:64
	v_pk_mul_f32 v[8:9], v[8:9], v[70:71] op_sel_hi:[1,0]
	v_pk_mul_f32 v[10:11], v[10:11], v[70:71] op_sel_hi:[1,0]
	v_pk_mul_f32 v[12:13], v[12:13], v[70:71] op_sel_hi:[1,0]
	v_pk_mul_f32 v[14:15], v[14:15], v[70:71] op_sel_hi:[1,0]
	v_cvt_pk_bf16_f32 v8, v8, v9
	v_cvt_pk_bf16_f32 v9, v10, v11
	v_cvt_pk_bf16_f32 v10, v12, v13
	v_cvt_pk_bf16_f32 v11, v14, v15
	s_nop 1
	v_permlane32_swap_b32_e32 v8, v10
	v_permlane32_swap_b32_e32 v9, v11
	global_store_dwordx4 v[78:79], v[8:11], off offset:96
	s_add_i32 s1, s1, s78
	s_add_i32 s0, s0, s78
	s_cmpk_gt_i32 s1, 0x1ff
	s_cbranch_scc1 .LBB0_443

; template <int EPI>
; __device__ __forceinline__ void gemm_epilogue(const f32x4 (&acc)[2][2][4][2], const Unit& u, int wr, int wc, int fr, int fq,
;                                               const EpiArgs& ea, const float (&rs_pre)[2][4]) {
;     ...
;     if (plain) {
; #pragma unroll
;       for (int ai = 0; ai < 2; ++ai)
; #pragma unroll
;         for (int m = 0; m < 4; ++m) {
;           const int row = row0 + ai * 128 + m * 16;
;           const float rs = rsr[ai][m];
; #pragma unroll
;           for (int bj = 0; bj < 2; ++bj)
; #pragma unroll
;             for (int n = 0; n < 2; ++n)
;               *reinterpret_cast<uint2*>(ea.out_bf + (size_t)row * LD + lc0 + bj * 32 + n * 16) = pack4(acc[ai][bj][m][n] * rs);
;         }
.LBB0_618:
	s_andn2_b64 vcc, exec, s[0:1]
	s_cbranch_vccnz .LBB0_569
	v_mbcnt_lo_u32_b32 v133, -1, 0
	v_mbcnt_hi_u32_b32 v133, -1, v133
	v_and_b32_e32 v133, 16, v133
	v_lshrrev_b32_e32 v132, 1, v133
	v_add_u32_e32 v132, v132, v133
	v_lshl_add_u32 v132, v178, 1, v132
	v_pk_mul_f32 v[126:127], v[126:127], v[176:177] op_sel_hi:[1,0]
	v_pk_mul_f32 v[128:129], v[128:129], v[176:177] op_sel_hi:[1,0]
	v_pk_mul_f32 v[122:123], v[122:123], v[176:177] op_sel_hi:[1,0]
	v_pk_mul_f32 v[124:125], v[124:125], v[176:177] op_sel_hi:[1,0]
	v_pk_mul_f32 v[118:119], v[118:119], v[176:177] op_sel_hi:[1,0]
	v_pk_mul_f32 v[120:121], v[120:121], v[176:177] op_sel_hi:[1,0]
	v_pk_mul_f32 v[114:115], v[114:115], v[176:177] op_sel_hi:[1,0]
	v_pk_mul_f32 v[116:117], v[116:117], v[176:177] op_sel_hi:[1,0]
	v_mul_u32_u24_e32 v131, s45, v172
	v_cvt_pk_bf16_f32 v126, v126, v127
	v_cvt_pk_bf16_f32 v127, v128, v129
	v_cvt_pk_bf16_f32 v128, v122, v123
	v_cvt_pk_bf16_f32 v129, v124, v125
	v_cvt_pk_bf16_f32 v118, v118, v119
	v_cvt_pk_bf16_f32 v119, v120, v121
	v_cvt_pk_bf16_f32 v120, v114, v115
	v_cvt_pk_bf16_f32 v121, v116, v117
	v_add_u32_e32 v131, v131, v132
	v_permlane16_swap_b32_e32 v126, v128
	v_permlane16_swap_b32_e32 v127, v129
	v_permlane16_swap_b32_e32 v118, v120
	v_permlane16_swap_b32_e32 v119, v121
	global_store_dwordx4 v131, v[126:129], s[42:43]
	global_store_dwordx4 v131, v[118:121], s[42:43] offset:64
	v_pk_mul_f32 v[108:109], v[108:109], v[174:175] op_sel_hi:[1,0]
	v_pk_mul_f32 v[110:111], v[110:111], v[174:175] op_sel_hi:[1,0]
	v_pk_mul_f32 v[104:105], v[104:105], v[174:175] op_sel_hi:[1,0]
	v_pk_mul_f32 v[106:107], v[106:107], v[174:175] op_sel_hi:[1,0]
	v_pk_mul_f32 v[100:101], v[100:101], v[174:175] op_sel_hi:[1,0]
	v_pk_mul_f32 v[102:103], v[102:103], v[174:175] op_sel_hi:[1,0]
	v_pk_mul_f32 v[96:97], v[96:97], v[174:175] op_sel_hi:[1,0]
	v_pk_mul_f32 v[98:99], v[98:99], v[174:175] op_sel_hi:[1,0]
	v_mul_u32_u24_e32 v131, s45, v168
	v_cvt_pk_bf16_f32 v108, v108, v109
	v_cvt_pk_bf16_f32 v109, v110, v111
	v_cvt_pk_bf16_f32 v110, v104, v105
	v_cvt_pk_bf16_f32 v111, v106, v107
	v_cvt_pk_bf16_f32 v100, v100, v101
	v_cvt_pk_bf16_f32 v101, v102, v103
	v_cvt_pk_bf16_f32 v102, v96, v97
	v_cvt_pk_bf16_f32 v103, v98, v99
	v_add_u32_e32 v131, v131, v132
	v_permlane16_swap_b32_e32 v108, v110
	v_permlane16_swap_b32_e32 v109, v111
	v_permlane16_swap_b32_e32 v100, v102
	v_permlane16_swap_b32_e32 v101, v103
	global_store_dwordx4 v131, v[108:111], s[42:43]
	global_store_dwordx4 v131, v[100:103], s[42:43] offset:64
	v_pk_mul_f32 v[92:93], v[92:93], v[170:171] op_sel_hi:[1,0]
	v_pk_mul_f32 v[94:95], v[94:95], v[170:171] op_sel_hi:[1,0]
	v_pk_mul_f32 v[88:89], v[88:89], v[170:171] op_sel_hi:[1,0]
	v_pk_mul_f32 v[90:91], v[90:91], v[170:171] op_sel_hi:[1,0]
	v_pk_mul_f32 v[84:85], v[84:85], v[170:171] op_sel_hi:[1,0]
	v_pk_mul_f32 v[86:87], v[86:87], v[170:171] op_sel_hi:[1,0]
	v_pk_mul_f32 v[80:81], v[80:81], v[170:171] op_sel_hi:[1,0]
	v_pk_mul_f32 v[82:83], v[82:83], v[170:171] op_sel_hi:[1,0]
	v_mul_u32_u24_e32 v131, s45, v164
	v_cvt_pk_bf16_f32 v92, v92, v93
	v_cvt_pk_bf16_f32 v93, v94, v95
	v_cvt_pk_bf16_f32 v94, v88, v89
	v_cvt_pk_bf16_f32 v95, v90, v91
	v_cvt_pk_bf16_f32 v84, v84, v85
	v_cvt_pk_bf16_f32 v85, v86, v87
	v_cvt_pk_bf16_f32 v86, v80, v81
	v_cvt_pk_bf16_f32 v87, v82, v83
	v_add_u32_e32 v131, v131, v132
	v_permlane16_swap_b32_e32 v92, v94
	v_permlane16_swap_b32_e32 v93, v95
	v_permlane16_swap_b32_e32 v84, v86
	v_permlane16_swap_b32_e32 v85, v87
	global_store_dwordx4 v131, v[92:95], s[42:43]
	global_store_dwordx4 v131, v[84:87], s[42:43] offset:64
	v_pk_mul_f32 v[76:77], v[76:77], v[166:167] op_sel_hi:[1,0]
	v_pk_mul_f32 v[78:79], v[78:79], v[166:167] op_sel_hi:[1,0]
	v_pk_mul_f32 v[72:73], v[72:73], v[166:167] op_sel_hi:[1,0]
	v_pk_mul_f32 v[74:75], v[74:75], v[166:167] op_sel_hi:[1,0]
	v_pk_mul_f32 v[68:69], v[68:69], v[166:167] op_sel_hi:[1,0]
	v_pk_mul_f32 v[70:71], v[70:71], v[166:167] op_sel_hi:[1,0]
	v_pk_mul_f32 v[64:65], v[64:65], v[166:167] op_sel_hi:[1,0]
	v_pk_mul_f32 v[66:67], v[66:67], v[166:167] op_sel_hi:[1,0]
	v_mul_u32_u24_e32 v131, s45, v160
	v_cvt_pk_bf16_f32 v76, v76, v77
	v_cvt_pk_bf16_f32 v77, v78, v79
	v_cvt_pk_bf16_f32 v78, v72, v73
	v_cvt_pk_bf16_f32 v79, v74, v75
	v_cvt_pk_bf16_f32 v68, v68, v69
	v_cvt_pk_bf16_f32 v69, v70, v71
	v_cvt_pk_bf16_f32 v70, v64, v65
	v_cvt_pk_bf16_f32 v71, v66, v67
	v_add_u32_e32 v131, v131, v132
	v_permlane16_swap_b32_e32 v76, v78
; template <int EPI>
; __device__ __forceinline__ void gemm_epilogue(const f32x4 (&acc)[2][2][4][2], const Unit& u, int wr, int wc, int fr, int fq,
;                                               const EpiArgs& ea, const float (&rs_pre)[2][4]) {
;     ...
;     if (plain) {
; #pragma unroll
;       for (int ai = 0; ai < 2; ++ai)
; #pragma unroll
;         for (int m = 0; m < 4; ++m) {
;           const int row = row0 + ai * 128 + m * 16;
;           const float rs = rsr[ai][m];
; #pragma unroll
;           for (int bj = 0; bj < 2; ++bj)
; #pragma unroll
;             for (int n = 0; n < 2; ++n)
;               *reinterpret_cast<uint2*>(ea.out_bf + (size_t)row * LD + lc0 + bj * 32 + n * 16) = pack4(acc[ai][bj][m][n] * rs);
;         }
	v_permlane16_swap_b32_e32 v77, v79
	v_permlane16_swap_b32_e32 v68, v70
	v_permlane16_swap_b32_e32 v69, v71
	global_store_dwordx4 v131, v[76:79], s[42:43]
	global_store_dwordx4 v131, v[68:71], s[42:43] offset:64
	v_pk_mul_f32 v[60:61], v[60:61], v[162:163] op_sel_hi:[1,0]
	v_pk_mul_f32 v[62:63], v[62:63], v[162:163] op_sel_hi:[1,0]
	v_pk_mul_f32 v[56:57], v[56:57], v[162:163] op_sel_hi:[1,0]
	v_pk_mul_f32 v[58:59], v[58:59], v[162:163] op_sel_hi:[1,0]
	v_pk_mul_f32 v[52:53], v[52:53], v[162:163] op_sel_hi:[1,0]
	v_pk_mul_f32 v[54:55], v[54:55], v[162:163] op_sel_hi:[1,0]
	v_pk_mul_f32 v[48:49], v[48:49], v[162:163] op_sel_hi:[1,0]
	v_pk_mul_f32 v[50:51], v[50:51], v[162:163] op_sel_hi:[1,0]
	v_mul_u32_u24_e32 v131, s45, v167
	v_cvt_pk_bf16_f32 v60, v60, v61
	v_cvt_pk_bf16_f32 v61, v62, v63
	v_cvt_pk_bf16_f32 v62, v56, v57
	v_cvt_pk_bf16_f32 v63, v58, v59
	v_cvt_pk_bf16_f32 v52, v52, v53
	v_cvt_pk_bf16_f32 v53, v54, v55
	v_cvt_pk_bf16_f32 v54, v48, v49
	v_cvt_pk_bf16_f32 v55, v50, v51
	v_add_u32_e32 v131, v131, v132
	v_permlane16_swap_b32_e32 v60, v62
	v_permlane16_swap_b32_e32 v61, v63
	v_permlane16_swap_b32_e32 v52, v54
	v_permlane16_swap_b32_e32 v53, v55
	global_store_dwordx4 v131, v[60:63], s[42:43]
	global_store_dwordx4 v131, v[52:55], s[42:43] offset:64
	v_pk_mul_f32 v[44:45], v[44:45], v[158:159] op_sel_hi:[1,0]
	v_pk_mul_f32 v[46:47], v[46:47], v[158:159] op_sel_hi:[1,0]
	v_pk_mul_f32 v[40:41], v[40:41], v[158:159] op_sel_hi:[1,0]
	v_pk_mul_f32 v[42:43], v[42:43], v[158:159] op_sel_hi:[1,0]
	v_pk_mul_f32 v[36:37], v[36:37], v[158:159] op_sel_hi:[1,0]
	v_pk_mul_f32 v[38:39], v[38:39], v[158:159] op_sel_hi:[1,0]
	v_pk_mul_f32 v[32:33], v[32:33], v[158:159] op_sel_hi:[1,0]
	v_pk_mul_f32 v[34:35], v[34:35], v[158:159] op_sel_hi:[1,0]
	v_mul_u32_u24_e32 v131, s45, v165
	v_cvt_pk_bf16_f32 v44, v44, v45
	v_cvt_pk_bf16_f32 v45, v46, v47
	v_cvt_pk_bf16_f32 v46, v40, v41
	v_cvt_pk_bf16_f32 v47, v42, v43
	v_cvt_pk_bf16_f32 v36, v36, v37
	v_cvt_pk_bf16_f32 v37, v38, v39
	v_cvt_pk_bf16_f32 v38, v32, v33
	v_cvt_pk_bf16_f32 v39, v34, v35
	v_add_u32_e32 v131, v131, v132
	v_permlane16_swap_b32_e32 v44, v46
	v_permlane16_swap_b32_e32 v45, v47
	v_permlane16_swap_b32_e32 v36, v38
	v_permlane16_swap_b32_e32 v37, v39
	global_store_dwordx4 v131, v[44:47], s[42:43]
	global_store_dwordx4 v131, v[36:39], s[42:43] offset:64
	v_pk_mul_f32 v[28:29], v[28:29], v[156:157] op_sel_hi:[1,0]
	v_pk_mul_f32 v[30:31], v[30:31], v[156:157] op_sel_hi:[1,0]
	v_pk_mul_f32 v[24:25], v[24:25], v[156:157] op_sel_hi:[1,0]
	v_pk_mul_f32 v[26:27], v[26:27], v[156:157] op_sel_hi:[1,0]
	v_pk_mul_f32 v[20:21], v[20:21], v[156:157] op_sel_hi:[1,0]
	v_pk_mul_f32 v[22:23], v[22:23], v[156:157] op_sel_hi:[1,0]
	v_pk_mul_f32 v[16:17], v[16:17], v[156:157] op_sel_hi:[1,0]
	v_pk_mul_f32 v[18:19], v[18:19], v[156:157] op_sel_hi:[1,0]
	v_mul_u32_u24_e32 v131, s45, v163
	v_cvt_pk_bf16_f32 v28, v28, v29
	v_cvt_pk_bf16_f32 v29, v30, v31
	v_cvt_pk_bf16_f32 v30, v24, v25
	v_cvt_pk_bf16_f32 v31, v26, v27
	v_cvt_pk_bf16_f32 v20, v20, v21
	v_cvt_pk_bf16_f32 v21, v22, v23
	v_cvt_pk_bf16_f32 v22, v16, v17
	v_cvt_pk_bf16_f32 v23, v18, v19
	v_add_u32_e32 v131, v131, v132
	v_permlane16_swap_b32_e32 v28, v30
	v_permlane16_swap_b32_e32 v29, v31
	v_permlane16_swap_b32_e32 v20, v22
	v_permlane16_swap_b32_e32 v21, v23
	global_store_dwordx4 v131, v[28:31], s[42:43]
	global_store_dwordx4 v131, v[20:23], s[42:43] offset:64
	v_pk_mul_f32 v[12:13], v[12:13], v[154:155] op_sel_hi:[1,0]
	v_pk_mul_f32 v[14:15], v[14:15], v[154:155] op_sel_hi:[1,0]
	v_pk_mul_f32 v[8:9], v[8:9], v[154:155] op_sel_hi:[1,0]
	v_pk_mul_f32 v[10:11], v[10:11], v[154:155] op_sel_hi:[1,0]
	v_pk_mul_f32 v[4:5], v[4:5], v[154:155] op_sel_hi:[1,0]
	v_pk_mul_f32 v[6:7], v[6:7], v[154:155] op_sel_hi:[1,0]
	v_pk_mul_f32 v[0:1], v[0:1], v[154:155] op_sel_hi:[1,0]
	v_pk_mul_f32 v[2:3], v[2:3], v[154:155] op_sel_hi:[1,0]
	v_mul_u32_u24_e32 v131, s45, v161
	v_cvt_pk_bf16_f32 v12, v12, v13
	v_cvt_pk_bf16_f32 v13, v14, v15
	v_cvt_pk_bf16_f32 v14, v8, v9
	v_cvt_pk_bf16_f32 v15, v10, v11
	v_cvt_pk_bf16_f32 v4, v4, v5
	v_cvt_pk_bf16_f32 v5, v6, v7
	v_cvt_pk_bf16_f32 v6, v0, v1
	v_cvt_pk_bf16_f32 v7, v2, v3
	v_add_u32_e32 v131, v131, v132
	v_permlane16_swap_b32_e32 v12, v14
	v_permlane16_swap_b32_e32 v13, v15
	v_permlane16_swap_b32_e32 v4, v6
	v_permlane16_swap_b32_e32 v5, v7
	global_store_dwordx4 v131, v[12:15], s[42:43]
	global_store_dwordx4 v131, v[4:7], s[42:43] offset:64
	s_branch .LBB0_569

; template <int EPI>
; __device__ __forceinline__ void gemm_epilogue(const f32x4 (&acc)[2][2][4][2], const Unit& u, int wr, int wc, int fr, int fq,
;                                               const EpiArgs& ea, const float (&rs_pre)[2][4]) {
;     ...
;     if (plain) {
; #pragma unroll
;       for (int ai = 0; ai < 2; ++ai)
; #pragma unroll
;         for (int m = 0; m < 4; ++m) {
;           const int row = row0 + ai * 128 + m * 16;
;           const float rs = rsr[ai][m];
; #pragma unroll
;           for (int bj = 0; bj < 2; ++bj)
; #pragma unroll
;             for (int n = 0; n < 2; ++n)
;               *reinterpret_cast<uint2*>(ea.out_bf + (size_t)row * LD + lc0 + bj * 32 + n * 16) = pack4(acc[ai][bj][m][n] * rs);
;         }
.LBB0_739:
	s_andn2_b64 vcc, exec, s[4:5]
	s_cbranch_vccnz .LBB0_686
	v_mbcnt_lo_u32_b32 v133, -1, 0
	v_mbcnt_hi_u32_b32 v133, -1, v133
	v_and_b32_e32 v133, 16, v133
	v_lshrrev_b32_e32 v132, 1, v133
	v_add_u32_e32 v132, v132, v133
	v_lshl_add_u32 v132, v190, 1, v132
	v_pk_mul_f32 v[126:127], v[126:127], v[188:189] op_sel_hi:[1,0]
	v_pk_mul_f32 v[128:129], v[128:129], v[188:189] op_sel_hi:[1,0]
	v_pk_mul_f32 v[122:123], v[122:123], v[188:189] op_sel_hi:[1,0]
	v_pk_mul_f32 v[124:125], v[124:125], v[188:189] op_sel_hi:[1,0]
	v_pk_mul_f32 v[118:119], v[118:119], v[188:189] op_sel_hi:[1,0]
	v_pk_mul_f32 v[120:121], v[120:121], v[188:189] op_sel_hi:[1,0]
	v_pk_mul_f32 v[114:115], v[114:115], v[188:189] op_sel_hi:[1,0]
	v_pk_mul_f32 v[116:117], v[116:117], v[188:189] op_sel_hi:[1,0]
	v_mul_u32_u24_e32 v131, s8, v186
	v_cvt_pk_bf16_f32 v126, v126, v127
	v_cvt_pk_bf16_f32 v127, v128, v129
	v_cvt_pk_bf16_f32 v128, v122, v123
	v_cvt_pk_bf16_f32 v129, v124, v125
	v_cvt_pk_bf16_f32 v118, v118, v119
	v_cvt_pk_bf16_f32 v119, v120, v121
	v_cvt_pk_bf16_f32 v120, v114, v115
	v_cvt_pk_bf16_f32 v121, v116, v117
	v_add_u32_e32 v131, v131, v132
	v_permlane16_swap_b32_e32 v126, v128
	v_permlane16_swap_b32_e32 v127, v129
	v_permlane16_swap_b32_e32 v118, v120
	v_permlane16_swap_b32_e32 v119, v121
	global_store_dwordx4 v131, v[126:129], s[42:43]
	global_store_dwordx4 v131, v[118:121], s[42:43] offset:64
	v_pk_mul_f32 v[108:109], v[108:109], v[182:183] op_sel_hi:[1,0]
	v_pk_mul_f32 v[110:111], v[110:111], v[182:183] op_sel_hi:[1,0]
	v_pk_mul_f32 v[104:105], v[104:105], v[182:183] op_sel_hi:[1,0]
	v_pk_mul_f32 v[106:107], v[106:107], v[182:183] op_sel_hi:[1,0]
	v_pk_mul_f32 v[100:101], v[100:101], v[182:183] op_sel_hi:[1,0]
	v_pk_mul_f32 v[102:103], v[102:103], v[182:183] op_sel_hi:[1,0]
	v_pk_mul_f32 v[96:97], v[96:97], v[182:183] op_sel_hi:[1,0]
	v_pk_mul_f32 v[98:99], v[98:99], v[182:183] op_sel_hi:[1,0]
	v_mul_u32_u24_e32 v131, s8, v178
	v_cvt_pk_bf16_f32 v108, v108, v109
	v_cvt_pk_bf16_f32 v109, v110, v111
	v_cvt_pk_bf16_f32 v110, v104, v105
	v_cvt_pk_bf16_f32 v111, v106, v107
	v_cvt_pk_bf16_f32 v100, v100, v101
	v_cvt_pk_bf16_f32 v101, v102, v103
	v_cvt_pk_bf16_f32 v102, v96, v97
	v_cvt_pk_bf16_f32 v103, v98, v99
	v_add_u32_e32 v131, v131, v132
	v_permlane16_swap_b32_e32 v108, v110
	v_permlane16_swap_b32_e32 v109, v111
	v_permlane16_swap_b32_e32 v100, v102
	v_permlane16_swap_b32_e32 v101, v103
	global_store_dwordx4 v131, v[108:111], s[42:43]
	global_store_dwordx4 v131, v[100:103], s[42:43] offset:64
	v_pk_mul_f32 v[92:93], v[92:93], v[180:181] op_sel_hi:[1,0]
	v_pk_mul_f32 v[94:95], v[94:95], v[180:181] op_sel_hi:[1,0]
	v_pk_mul_f32 v[88:89], v[88:89], v[180:181] op_sel_hi:[1,0]
	v_pk_mul_f32 v[90:91], v[90:91], v[180:181] op_sel_hi:[1,0]
	v_pk_mul_f32 v[84:85], v[84:85], v[180:181] op_sel_hi:[1,0]
	v_pk_mul_f32 v[86:87], v[86:87], v[180:181] op_sel_hi:[1,0]
	v_pk_mul_f32 v[80:81], v[80:81], v[180:181] op_sel_hi:[1,0]
	v_pk_mul_f32 v[82:83], v[82:83], v[180:181] op_sel_hi:[1,0]
	v_mul_u32_u24_e32 v131, s8, v174
	v_cvt_pk_bf16_f32 v92, v92, v93
	v_cvt_pk_bf16_f32 v93, v94, v95
	v_cvt_pk_bf16_f32 v94, v88, v89
	v_cvt_pk_bf16_f32 v95, v90, v91
	v_cvt_pk_bf16_f32 v84, v84, v85
	v_cvt_pk_bf16_f32 v85, v86, v87
	v_cvt_pk_bf16_f32 v86, v80, v81
	v_cvt_pk_bf16_f32 v87, v82, v83
	v_add_u32_e32 v131, v131, v132
	v_permlane16_swap_b32_e32 v92, v94
	v_permlane16_swap_b32_e32 v93, v95
	v_permlane16_swap_b32_e32 v84, v86
	v_permlane16_swap_b32_e32 v85, v87
	global_store_dwordx4 v131, v[92:95], s[42:43]
	global_store_dwordx4 v131, v[84:87], s[42:43] offset:64
	v_pk_mul_f32 v[76:77], v[76:77], v[176:177] op_sel_hi:[1,0]
	v_pk_mul_f32 v[78:79], v[78:79], v[176:177] op_sel_hi:[1,0]
	v_pk_mul_f32 v[72:73], v[72:73], v[176:177] op_sel_hi:[1,0]
	v_pk_mul_f32 v[74:75], v[74:75], v[176:177] op_sel_hi:[1,0]
	v_pk_mul_f32 v[68:69], v[68:69], v[176:177] op_sel_hi:[1,0]
	v_pk_mul_f32 v[70:71], v[70:71], v[176:177] op_sel_hi:[1,0]
	v_pk_mul_f32 v[64:65], v[64:65], v[176:177] op_sel_hi:[1,0]
	v_pk_mul_f32 v[66:67], v[66:67], v[176:177] op_sel_hi:[1,0]
	v_mul_u32_u24_e32 v131, s8, v170
	v_cvt_pk_bf16_f32 v76, v76, v77
	v_cvt_pk_bf16_f32 v77, v78, v79
	v_cvt_pk_bf16_f32 v78, v72, v73
	v_cvt_pk_bf16_f32 v79, v74, v75
	v_cvt_pk_bf16_f32 v68, v68, v69
	v_cvt_pk_bf16_f32 v69, v70, v71
	v_cvt_pk_bf16_f32 v70, v64, v65
	v_cvt_pk_bf16_f32 v71, v66, v67
	v_add_u32_e32 v131, v131, v132
	v_permlane16_swap_b32_e32 v76, v78
; template <int EPI>
; __device__ __forceinline__ void gemm_epilogue(const f32x4 (&acc)[2][2][4][2], const Unit& u, int wr, int wc, int fr, int fq,
;                                               const EpiArgs& ea, const float (&rs_pre)[2][4]) {
;     ...
;     if (plain) {
; #pragma unroll
;       for (int ai = 0; ai < 2; ++ai)
; #pragma unroll
;         for (int m = 0; m < 4; ++m) {
;           const int row = row0 + ai * 128 + m * 16;
;           const float rs = rsr[ai][m];
; #pragma unroll
;           for (int bj = 0; bj < 2; ++bj)
; #pragma unroll
;             for (int n = 0; n < 2; ++n)
;               *reinterpret_cast<uint2*>(ea.out_bf + (size_t)row * LD + lc0 + bj * 32 + n * 16) = pack4(acc[ai][bj][m][n] * rs);
;         }
	v_permlane16_swap_b32_e32 v77, v79
	v_permlane16_swap_b32_e32 v68, v70
	v_permlane16_swap_b32_e32 v69, v71
	global_store_dwordx4 v131, v[76:79], s[42:43]
	global_store_dwordx4 v131, v[68:71], s[42:43] offset:64
	v_pk_mul_f32 v[60:61], v[60:61], v[172:173] op_sel_hi:[1,0]
	v_pk_mul_f32 v[62:63], v[62:63], v[172:173] op_sel_hi:[1,0]
	v_pk_mul_f32 v[56:57], v[56:57], v[172:173] op_sel_hi:[1,0]
	v_pk_mul_f32 v[58:59], v[58:59], v[172:173] op_sel_hi:[1,0]
	v_pk_mul_f32 v[52:53], v[52:53], v[172:173] op_sel_hi:[1,0]
	v_pk_mul_f32 v[54:55], v[54:55], v[172:173] op_sel_hi:[1,0]
	v_pk_mul_f32 v[48:49], v[48:49], v[172:173] op_sel_hi:[1,0]
	v_pk_mul_f32 v[50:51], v[50:51], v[172:173] op_sel_hi:[1,0]
	v_mul_u32_u24_e32 v131, s8, v166
	v_cvt_pk_bf16_f32 v60, v60, v61
	v_cvt_pk_bf16_f32 v61, v62, v63
	v_cvt_pk_bf16_f32 v62, v56, v57
	v_cvt_pk_bf16_f32 v63, v58, v59
	v_cvt_pk_bf16_f32 v52, v52, v53
	v_cvt_pk_bf16_f32 v53, v54, v55
	v_cvt_pk_bf16_f32 v54, v48, v49
	v_cvt_pk_bf16_f32 v55, v50, v51
	v_add_u32_e32 v131, v131, v132
	v_permlane16_swap_b32_e32 v60, v62
	v_permlane16_swap_b32_e32 v61, v63
	v_permlane16_swap_b32_e32 v52, v54
	v_permlane16_swap_b32_e32 v53, v55
	global_store_dwordx4 v131, v[60:63], s[42:43]
	global_store_dwordx4 v131, v[52:55], s[42:43] offset:64
	v_pk_mul_f32 v[44:45], v[44:45], v[168:169] op_sel_hi:[1,0]
	v_pk_mul_f32 v[46:47], v[46:47], v[168:169] op_sel_hi:[1,0]
	v_pk_mul_f32 v[40:41], v[40:41], v[168:169] op_sel_hi:[1,0]
	v_pk_mul_f32 v[42:43], v[42:43], v[168:169] op_sel_hi:[1,0]
	v_pk_mul_f32 v[36:37], v[36:37], v[168:169] op_sel_hi:[1,0]
	v_pk_mul_f32 v[38:39], v[38:39], v[168:169] op_sel_hi:[1,0]
	v_pk_mul_f32 v[32:33], v[32:33], v[168:169] op_sel_hi:[1,0]
	v_pk_mul_f32 v[34:35], v[34:35], v[168:169] op_sel_hi:[1,0]
	v_mul_u32_u24_e32 v131, s8, v162
	v_cvt_pk_bf16_f32 v44, v44, v45
	v_cvt_pk_bf16_f32 v45, v46, v47
	v_cvt_pk_bf16_f32 v46, v40, v41
	v_cvt_pk_bf16_f32 v47, v42, v43
	v_cvt_pk_bf16_f32 v36, v36, v37
	v_cvt_pk_bf16_f32 v37, v38, v39
	v_cvt_pk_bf16_f32 v38, v32, v33
	v_cvt_pk_bf16_f32 v39, v34, v35
	v_add_u32_e32 v131, v131, v132
	v_permlane16_swap_b32_e32 v44, v46
	v_permlane16_swap_b32_e32 v45, v47
	v_permlane16_swap_b32_e32 v36, v38
	v_permlane16_swap_b32_e32 v37, v39
	global_store_dwordx4 v131, v[44:47], s[42:43]
	global_store_dwordx4 v131, v[36:39], s[42:43] offset:64
	v_pk_mul_f32 v[28:29], v[28:29], v[164:165] op_sel_hi:[1,0]
	v_pk_mul_f32 v[30:31], v[30:31], v[164:165] op_sel_hi:[1,0]
	v_pk_mul_f32 v[24:25], v[24:25], v[164:165] op_sel_hi:[1,0]
	v_pk_mul_f32 v[26:27], v[26:27], v[164:165] op_sel_hi:[1,0]
	v_pk_mul_f32 v[20:21], v[20:21], v[164:165] op_sel_hi:[1,0]
	v_pk_mul_f32 v[22:23], v[22:23], v[164:165] op_sel_hi:[1,0]
	v_pk_mul_f32 v[16:17], v[16:17], v[164:165] op_sel_hi:[1,0]
	v_pk_mul_f32 v[18:19], v[18:19], v[164:165] op_sel_hi:[1,0]
	v_mul_u32_u24_e32 v131, s8, v158
	v_cvt_pk_bf16_f32 v28, v28, v29
	v_cvt_pk_bf16_f32 v29, v30, v31
	v_cvt_pk_bf16_f32 v30, v24, v25
	v_cvt_pk_bf16_f32 v31, v26, v27
	v_cvt_pk_bf16_f32 v20, v20, v21
	v_cvt_pk_bf16_f32 v21, v22, v23
	v_cvt_pk_bf16_f32 v22, v16, v17
	v_cvt_pk_bf16_f32 v23, v18, v19
	v_add_u32_e32 v131, v131, v132
	v_permlane16_swap_b32_e32 v28, v30
	v_permlane16_swap_b32_e32 v29, v31
	v_permlane16_swap_b32_e32 v20, v22
	v_permlane16_swap_b32_e32 v21, v23
	global_store_dwordx4 v131, v[28:31], s[42:43]
	global_store_dwordx4 v131, v[20:23], s[42:43] offset:64
	v_pk_mul_f32 v[12:13], v[12:13], v[160:161] op_sel_hi:[1,0]
	v_pk_mul_f32 v[14:15], v[14:15], v[160:161] op_sel_hi:[1,0]
	v_pk_mul_f32 v[8:9], v[8:9], v[160:161] op_sel_hi:[1,0]
	v_pk_mul_f32 v[10:11], v[10:11], v[160:161] op_sel_hi:[1,0]
	v_pk_mul_f32 v[4:5], v[4:5], v[160:161] op_sel_hi:[1,0]
	v_pk_mul_f32 v[6:7], v[6:7], v[160:161] op_sel_hi:[1,0]
	v_pk_mul_f32 v[0:1], v[0:1], v[160:161] op_sel_hi:[1,0]
	v_pk_mul_f32 v[2:3], v[2:3], v[160:161] op_sel_hi:[1,0]
	v_mul_u32_u24_e32 v131, s8, v156
	v_cvt_pk_bf16_f32 v12, v12, v13
	v_cvt_pk_bf16_f32 v13, v14, v15
	v_cvt_pk_bf16_f32 v14, v8, v9
	v_cvt_pk_bf16_f32 v15, v10, v11
	v_cvt_pk_bf16_f32 v4, v4, v5
	v_cvt_pk_bf16_f32 v5, v6, v7
	v_cvt_pk_bf16_f32 v6, v0, v1
	v_cvt_pk_bf16_f32 v7, v2, v3
	v_add_u32_e32 v131, v131, v132
	v_permlane16_swap_b32_e32 v12, v14
	v_permlane16_swap_b32_e32 v13, v15
	v_permlane16_swap_b32_e32 v4, v6
	v_permlane16_swap_b32_e32 v5, v7
	global_store_dwordx4 v131, v[12:15], s[42:43]
	global_store_dwordx4 v131, v[4:7], s[42:43] offset:64
	s_branch .LBB0_686

; __device__ __forceinline__ float sigmoidf_(float x) { return __builtin_amdgcn_rcpf(1.f + __expf(-x)); }
; __device__ __forceinline__ float rstd_of(float ssv) { return rsqrtf(ssv * (1.f / 1024.f) + EPS); }
; template <int EPI>
; __device__ __forceinline__ void gemm_epilogue(const f32x4 (&acc)[2][2][4][2], const Unit& u, int wr, int wc, int fr, int fq,
;                                               const EpiArgs& ea, const float (&rs_pre)[2][4]) {
;     ...
;   if constexpr (EPI == EPI_SWIGLU || EPI == EPI_PLEGATE || EPI == EPI_EVEN || EPI == EPI_ODD) {
; #pragma unroll
;     for (int ai = 0; ai < 2; ++ai)
; #pragma unroll
;       for (int m = 0; m < 4; ++m)
;         rsr[ai][m] = (EPI == EPI_SWIGLU || EPI == EPI_PLEGATE) ? rs_pre[ai][m] : ea.ss_in[row0 + ai * 128 + m * 16];
; #pragma unroll
;     for (int ai = 0; ai < 2; ++ai)
; #pragma unroll
;       for (int m = 0; m < 4; ++m) rsr[ai][m] = rstd_of(rsr[ai][m]);
;   }
;   if constexpr (EPI == EPI_SWIGLU) {
; #pragma unroll
;     for (int ai = 0; ai < 2; ++ai)
; #pragma unroll
;       for (int m = 0; m < 4; ++m) {
;         const int row = row0 + ai * 128 + m * 16;
;         const float rs = rsr[ai][m];
;         u16* rowp = ea.out_bf + (size_t)row * 2816 + u.pn * 128 + wc * 32 + 8 * fq;
;         uint2 hp2[2];
; #pragma unroll
;         for (int n = 0; n < 2; ++n) {
;           f32x4 g = acc[ai][0][m][n] * rs, uu = acc[ai][1][m][n] * rs, h;
; #pragma unroll
;           for (int i = 0; i < 4; ++i) h[i] = g[i] * sigmoidf_(g[i]) * uu[i];
;           hp2[n] = pack4(h);
;         }
;         *reinterpret_cast<uint4*>(rowp) = make_uint4(hp2[0].x, hp2[0].y, hp2[1].x, hp2[1].y);
;       }
.LBB0_918:
	v_fmamk_f32 v162, v149, 0x3a800000, v218
	v_fmamk_f32 v163, v148, 0x3a800000, v218
	v_fmamk_f32 v164, v147, 0x3a800000, v218
	v_fmamk_f32 v165, v146, 0x3a800000, v218
	v_fmamk_f32 v166, v143, 0x3a800000, v218
	v_fmamk_f32 v167, v142, 0x3a800000, v218
	v_fmamk_f32 v168, v141, 0x3a800000, v218
	v_fmamk_f32 v169, v140, 0x3a800000, v218
	v_rsq_f32_e32 v162, v162
	v_rsq_f32_e32 v163, v163
	v_rsq_f32_e32 v164, v164
	v_rsq_f32_e32 v165, v165
	v_rsq_f32_e32 v166, v166
	v_rsq_f32_e32 v167, v167
	v_rsq_f32_e32 v168, v168
	v_rsq_f32_e32 v169, v169
	v_lshl_add_u32 v148, s64, 8, v113
	s_lshl_b32 s36, s72, 7
	s_ashr_i32 s37, s36, 31
	s_lshl_b64 s[60:61], s[36:37], 1
	v_readlane_b32 s12, v254, 16
	s_lshl_b32 s94, s12, 1
	v_mul_u32_u24_e32 v160, s3, v148
	v_add_u32_e32 v160, s60, v160
	v_add_u32_e32 v160, s94, v160
	v_add_u32_e32 v160, v160, v138
	v_mul_f32_e32 v170, 0xbfb8aa3b, v162
	v_mul_f32_e32 v172, v162, v162
	v_pk_mul_f32 v[174:175], v[126:127], v[170:171] op_sel_hi:[1,0]
	v_pk_mul_f32 v[176:177], v[128:129], v[170:171] op_sel_hi:[1,0]
	v_exp_f32_e32 v174, v174
	v_exp_f32_e32 v176, v176
	v_exp_f32_e32 v175, v175
	v_exp_f32_e32 v177, v177
	v_pk_mul_f32 v[122:123], v[126:127], v[122:123]
	v_pk_mul_f32 v[124:125], v[128:129], v[124:125]
	v_pk_add_f32 v[174:175], v[174:175], 1.0 op_sel_hi:[1,0]
	v_pk_add_f32 v[176:177], v[176:177], 1.0 op_sel_hi:[1,0]
	v_rcp_f32_e32 v174, v174
	v_rcp_f32_e32 v176, v176
	v_rcp_f32_e32 v175, v175
	v_rcp_f32_e32 v177, v177
	v_pk_mul_f32 v[174:175], v[174:175], v[172:173] op_sel_hi:[1,0]
	v_pk_mul_f32 v[176:177], v[176:177], v[172:173] op_sel_hi:[1,0]
	v_pk_mul_f32 v[126:127], v[122:123], v[174:175]
	v_pk_mul_f32 v[128:129], v[124:125], v[176:177]
	v_pk_mul_f32 v[174:175], v[118:119], v[170:171] op_sel_hi:[1,0]
	v_pk_mul_f32 v[176:177], v[120:121], v[170:171] op_sel_hi:[1,0]
	v_exp_f32_e32 v174, v174
	v_exp_f32_e32 v176, v176
	v_exp_f32_e32 v175, v175
	v_exp_f32_e32 v177, v177
	v_pk_mul_f32 v[114:115], v[118:119], v[114:115]
	v_pk_mul_f32 v[116:117], v[120:121], v[116:117]
	v_pk_add_f32 v[174:175], v[174:175], 1.0 op_sel_hi:[1,0]
	v_pk_add_f32 v[176:177], v[176:177], 1.0 op_sel_hi:[1,0]
	v_rcp_f32_e32 v174, v174
	v_rcp_f32_e32 v176, v176
	v_rcp_f32_e32 v175, v175
	v_rcp_f32_e32 v177, v177
	v_pk_mul_f32 v[174:175], v[174:175], v[172:173] op_sel_hi:[1,0]
	v_pk_mul_f32 v[176:177], v[176:177], v[172:173] op_sel_hi:[1,0]
	v_pk_mul_f32 v[118:119], v[114:115], v[174:175]
	v_pk_mul_f32 v[120:121], v[116:117], v[176:177]
	v_cvt_pk_bf16_f32 v126, v126, v127
	v_cvt_pk_bf16_f32 v127, v128, v129
	v_cvt_pk_bf16_f32 v128, v118, v119
	v_cvt_pk_bf16_f32 v129, v120, v121
	global_store_dwordx4 v160, v[126:129], s[42:43]
	v_mul_f32_e32 v170, 0xbfb8aa3b, v163
	v_mul_f32_e32 v172, v163, v163
	v_pk_mul_f32 v[174:175], v[108:109], v[170:171] op_sel_hi:[1,0]
	v_pk_mul_f32 v[176:177], v[110:111], v[170:171] op_sel_hi:[1,0]
	v_exp_f32_e32 v174, v174
	v_exp_f32_e32 v176, v176
	v_exp_f32_e32 v175, v175
	v_exp_f32_e32 v177, v177
	v_pk_mul_f32 v[104:105], v[108:109], v[104:105]
	v_pk_mul_f32 v[106:107], v[110:111], v[106:107]
	v_pk_add_f32 v[174:175], v[174:175], 1.0 op_sel_hi:[1,0]
	v_pk_add_f32 v[176:177], v[176:177], 1.0 op_sel_hi:[1,0]
	v_rcp_f32_e32 v174, v174
	v_rcp_f32_e32 v176, v176
	v_rcp_f32_e32 v175, v175
	v_rcp_f32_e32 v177, v177
	v_pk_mul_f32 v[174:175], v[174:175], v[172:173] op_sel_hi:[1,0]
	v_pk_mul_f32 v[176:177], v[176:177], v[172:173] op_sel_hi:[1,0]
	v_pk_mul_f32 v[108:109], v[104:105], v[174:175]
	v_pk_mul_f32 v[110:111], v[106:107], v[176:177]
	v_pk_mul_f32 v[174:175], v[100:101], v[170:171] op_sel_hi:[1,0]
	v_pk_mul_f32 v[176:177], v[102:103], v[170:171] op_sel_hi:[1,0]
	v_exp_f32_e32 v174, v174
	v_exp_f32_e32 v176, v176
	v_exp_f32_e32 v175, v175
	v_exp_f32_e32 v177, v177
	v_pk_mul_f32 v[96:97], v[100:101], v[96:97]
	v_pk_mul_f32 v[98:99], v[102:103], v[98:99]
	v_pk_add_f32 v[174:175], v[174:175], 1.0 op_sel_hi:[1,0]
	v_pk_add_f32 v[176:177], v[176:177], 1.0 op_sel_hi:[1,0]
	v_rcp_f32_e32 v174, v174
	v_rcp_f32_e32 v176, v176
	v_rcp_f32_e32 v175, v175
	v_rcp_f32_e32 v177, v177
	v_pk_mul_f32 v[174:175], v[174:175], v[172:173] op_sel_hi:[1,0]
	v_pk_mul_f32 v[176:177], v[176:177], v[172:173] op_sel_hi:[1,0]
	v_pk_mul_f32 v[100:101], v[96:97], v[174:175]
	v_pk_mul_f32 v[102:103], v[98:99], v[176:177]
	v_cvt_pk_bf16_f32 v108, v108, v109
	v_cvt_pk_bf16_f32 v109, v110, v111
	v_cvt_pk_bf16_f32 v110, v100, v101
	v_cvt_pk_bf16_f32 v111, v102, v103
	s_mul_i32 s37, s3, 16
	v_add_u32_e32 v161, s37, v160
	global_store_dwordx4 v161, v[108:111], s[42:43]
	v_mul_f32_e32 v170, 0xbfb8aa3b, v164
	v_mul_f32_e32 v172, v164, v164
	v_pk_mul_f32 v[174:175], v[92:93], v[170:171] op_sel_hi:[1,0]
	v_pk_mul_f32 v[176:177], v[94:95], v[170:171] op_sel_hi:[1,0]
	v_exp_f32_e32 v174, v174
	v_exp_f32_e32 v176, v176
	v_exp_f32_e32 v175, v175
	v_exp_f32_e32 v177, v177
	v_pk_mul_f32 v[88:89], v[92:93], v[88:89]
	v_pk_mul_f32 v[90:91], v[94:95], v[90:91]
	v_pk_add_f32 v[174:175], v[174:175], 1.0 op_sel_hi:[1,0]
	v_pk_add_f32 v[176:177], v[176:177], 1.0 op_sel_hi:[1,0]
	v_rcp_f32_e32 v174, v174
	v_rcp_f32_e32 v176, v176
	v_rcp_f32_e32 v175, v175
	v_rcp_f32_e32 v177, v177
	v_pk_mul_f32 v[174:175], v[174:175], v[172:173] op_sel_hi:[1,0]
	v_pk_mul_f32 v[176:177], v[176:177], v[172:173] op_sel_hi:[1,0]
	v_pk_mul_f32 v[92:93], v[88:89], v[174:175]
	v_pk_mul_f32 v[94:95], v[90:91], v[176:177]
	v_pk_mul_f32 v[174:175], v[84:85], v[170:171] op_sel_hi:[1,0]
	v_pk_mul_f32 v[176:177], v[86:87], v[170:171] op_sel_hi:[1,0]
	v_exp_f32_e32 v174, v174
	v_exp_f32_e32 v176, v176
	v_exp_f32_e32 v175, v175
	v_exp_f32_e32 v177, v177
	v_pk_mul_f32 v[80:81], v[84:85], v[80:81]
; __device__ __forceinline__ float sigmoidf_(float x) { return __builtin_amdgcn_rcpf(1.f + __expf(-x)); }
; template <int EPI>
; __device__ __forceinline__ void gemm_epilogue(const f32x4 (&acc)[2][2][4][2], const Unit& u, int wr, int wc, int fr, int fq,
;                                               const EpiArgs& ea, const float (&rs_pre)[2][4]) {
;     ...
;   if constexpr (EPI == EPI_SWIGLU) {
; #pragma unroll
;     for (int ai = 0; ai < 2; ++ai)
; #pragma unroll
;       for (int m = 0; m < 4; ++m) {
;         const int row = row0 + ai * 128 + m * 16;
;         const float rs = rsr[ai][m];
;         u16* rowp = ea.out_bf + (size_t)row * 2816 + u.pn * 128 + wc * 32 + 8 * fq;
;         uint2 hp2[2];
; #pragma unroll
;         for (int n = 0; n < 2; ++n) {
;           f32x4 g = acc[ai][0][m][n] * rs, uu = acc[ai][1][m][n] * rs, h;
; #pragma unroll
;           for (int i = 0; i < 4; ++i) h[i] = g[i] * sigmoidf_(g[i]) * uu[i];
;           hp2[n] = pack4(h);
;         }
;         *reinterpret_cast<uint4*>(rowp) = make_uint4(hp2[0].x, hp2[0].y, hp2[1].x, hp2[1].y);
;       }
	v_pk_mul_f32 v[82:83], v[86:87], v[82:83]
	v_pk_add_f32 v[174:175], v[174:175], 1.0 op_sel_hi:[1,0]
	v_pk_add_f32 v[176:177], v[176:177], 1.0 op_sel_hi:[1,0]
	v_rcp_f32_e32 v174, v174
	v_rcp_f32_e32 v176, v176
	v_rcp_f32_e32 v175, v175
	v_rcp_f32_e32 v177, v177
	v_pk_mul_f32 v[174:175], v[174:175], v[172:173] op_sel_hi:[1,0]
	v_pk_mul_f32 v[176:177], v[176:177], v[172:173] op_sel_hi:[1,0]
	v_pk_mul_f32 v[84:85], v[80:81], v[174:175]
	v_pk_mul_f32 v[86:87], v[82:83], v[176:177]
	v_cvt_pk_bf16_f32 v92, v92, v93
	v_cvt_pk_bf16_f32 v93, v94, v95
	v_cvt_pk_bf16_f32 v94, v84, v85
	v_cvt_pk_bf16_f32 v95, v86, v87
	s_mul_i32 s37, s3, 32
	v_add_u32_e32 v161, s37, v160
	global_store_dwordx4 v161, v[92:95], s[42:43]
	v_mul_f32_e32 v170, 0xbfb8aa3b, v165
	v_mul_f32_e32 v172, v165, v165
	v_pk_mul_f32 v[174:175], v[76:77], v[170:171] op_sel_hi:[1,0]
	v_pk_mul_f32 v[176:177], v[78:79], v[170:171] op_sel_hi:[1,0]
	v_exp_f32_e32 v174, v174
	v_exp_f32_e32 v176, v176
	v_exp_f32_e32 v175, v175
	v_exp_f32_e32 v177, v177
	v_pk_mul_f32 v[72:73], v[76:77], v[72:73]
	v_pk_mul_f32 v[74:75], v[78:79], v[74:75]
	v_pk_add_f32 v[174:175], v[174:175], 1.0 op_sel_hi:[1,0]
	v_pk_add_f32 v[176:177], v[176:177], 1.0 op_sel_hi:[1,0]
	v_rcp_f32_e32 v174, v174
	v_rcp_f32_e32 v176, v176
	v_rcp_f32_e32 v175, v175
	v_rcp_f32_e32 v177, v177
	v_pk_mul_f32 v[174:175], v[174:175], v[172:173] op_sel_hi:[1,0]
	v_pk_mul_f32 v[176:177], v[176:177], v[172:173] op_sel_hi:[1,0]
	v_pk_mul_f32 v[76:77], v[72:73], v[174:175]
	v_pk_mul_f32 v[78:79], v[74:75], v[176:177]
	v_pk_mul_f32 v[174:175], v[68:69], v[170:171] op_sel_hi:[1,0]
	v_pk_mul_f32 v[176:177], v[70:71], v[170:171] op_sel_hi:[1,0]
	v_exp_f32_e32 v174, v174
	v_exp_f32_e32 v176, v176
	v_exp_f32_e32 v175, v175
	v_exp_f32_e32 v177, v177
	v_pk_mul_f32 v[64:65], v[68:69], v[64:65]
	v_pk_mul_f32 v[66:67], v[70:71], v[66:67]
	v_pk_add_f32 v[174:175], v[174:175], 1.0 op_sel_hi:[1,0]
	v_pk_add_f32 v[176:177], v[176:177], 1.0 op_sel_hi:[1,0]
	v_rcp_f32_e32 v174, v174
	v_rcp_f32_e32 v176, v176
	v_rcp_f32_e32 v175, v175
	v_rcp_f32_e32 v177, v177
	v_pk_mul_f32 v[174:175], v[174:175], v[172:173] op_sel_hi:[1,0]
	v_pk_mul_f32 v[176:177], v[176:177], v[172:173] op_sel_hi:[1,0]
	v_pk_mul_f32 v[68:69], v[64:65], v[174:175]
	v_pk_mul_f32 v[70:71], v[66:67], v[176:177]
	v_cvt_pk_bf16_f32 v76, v76, v77
	v_cvt_pk_bf16_f32 v77, v78, v79
	v_cvt_pk_bf16_f32 v78, v68, v69
	v_cvt_pk_bf16_f32 v79, v70, v71
	s_mul_i32 s37, s3, 48
	v_add_u32_e32 v161, s37, v160
	global_store_dwordx4 v161, v[76:79], s[42:43]
	v_mul_f32_e32 v170, 0xbfb8aa3b, v166
	v_mul_f32_e32 v172, v166, v166
	v_pk_mul_f32 v[174:175], v[60:61], v[170:171] op_sel_hi:[1,0]
	v_pk_mul_f32 v[176:177], v[62:63], v[170:171] op_sel_hi:[1,0]
	v_exp_f32_e32 v174, v174
	v_exp_f32_e32 v176, v176
	v_exp_f32_e32 v175, v175
	v_exp_f32_e32 v177, v177
	v_pk_mul_f32 v[56:57], v[60:61], v[56:57]
	v_pk_mul_f32 v[58:59], v[62:63], v[58:59]
	v_pk_add_f32 v[174:175], v[174:175], 1.0 op_sel_hi:[1,0]
	v_pk_add_f32 v[176:177], v[176:177], 1.0 op_sel_hi:[1,0]
	v_rcp_f32_e32 v174, v174
	v_rcp_f32_e32 v176, v176
	v_rcp_f32_e32 v175, v175
	v_rcp_f32_e32 v177, v177
	v_pk_mul_f32 v[174:175], v[174:175], v[172:173] op_sel_hi:[1,0]
	v_pk_mul_f32 v[176:177], v[176:177], v[172:173] op_sel_hi:[1,0]
	v_pk_mul_f32 v[60:61], v[56:57], v[174:175]
	v_pk_mul_f32 v[62:63], v[58:59], v[176:177]
	v_pk_mul_f32 v[174:175], v[52:53], v[170:171] op_sel_hi:[1,0]
	v_pk_mul_f32 v[176:177], v[54:55], v[170:171] op_sel_hi:[1,0]
	v_exp_f32_e32 v174, v174
	v_exp_f32_e32 v176, v176
	v_exp_f32_e32 v175, v175
	v_exp_f32_e32 v177, v177
	v_pk_mul_f32 v[48:49], v[52:53], v[48:49]
	v_pk_mul_f32 v[50:51], v[54:55], v[50:51]
	v_pk_add_f32 v[174:175], v[174:175], 1.0 op_sel_hi:[1,0]
	v_pk_add_f32 v[176:177], v[176:177], 1.0 op_sel_hi:[1,0]
	v_rcp_f32_e32 v174, v174
	v_rcp_f32_e32 v176, v176
	v_rcp_f32_e32 v175, v175
	v_rcp_f32_e32 v177, v177
	v_pk_mul_f32 v[174:175], v[174:175], v[172:173] op_sel_hi:[1,0]
	v_pk_mul_f32 v[176:177], v[176:177], v[172:173] op_sel_hi:[1,0]
	v_pk_mul_f32 v[52:53], v[48:49], v[174:175]
	v_pk_mul_f32 v[54:55], v[50:51], v[176:177]
	v_cvt_pk_bf16_f32 v60, v60, v61
	v_cvt_pk_bf16_f32 v61, v62, v63
	v_cvt_pk_bf16_f32 v62, v52, v53
	v_cvt_pk_bf16_f32 v63, v54, v55
	s_mul_i32 s37, s3, 128
	v_add_u32_e32 v161, s37, v160
	global_store_dwordx4 v161, v[60:63], s[42:43]
	v_mul_f32_e32 v170, 0xbfb8aa3b, v167
	v_mul_f32_e32 v172, v167, v167
	v_pk_mul_f32 v[174:175], v[44:45], v[170:171] op_sel_hi:[1,0]
	v_pk_mul_f32 v[176:177], v[46:47], v[170:171] op_sel_hi:[1,0]
	v_exp_f32_e32 v174, v174
	v_exp_f32_e32 v176, v176
	v_exp_f32_e32 v175, v175
	v_exp_f32_e32 v177, v177
	v_pk_mul_f32 v[40:41], v[44:45], v[40:41]
	v_pk_mul_f32 v[42:43], v[46:47], v[42:43]
	v_pk_add_f32 v[174:175], v[174:175], 1.0 op_sel_hi:[1,0]
	v_pk_add_f32 v[176:177], v[176:177], 1.0 op_sel_hi:[1,0]
	v_rcp_f32_e32 v174, v174
	v_rcp_f32_e32 v176, v176
	v_rcp_f32_e32 v175, v175
	v_rcp_f32_e32 v177, v177
	v_pk_mul_f32 v[174:175], v[174:175], v[172:173] op_sel_hi:[1,0]
	v_pk_mul_f32 v[176:177], v[176:177], v[172:173] op_sel_hi:[1,0]
	v_pk_mul_f32 v[44:45], v[40:41], v[174:175]
	v_pk_mul_f32 v[46:47], v[42:43], v[176:177]
; __device__ __forceinline__ float sigmoidf_(float x) { return __builtin_amdgcn_rcpf(1.f + __expf(-x)); }
; template <int EPI>
; __device__ __forceinline__ void gemm_epilogue(const f32x4 (&acc)[2][2][4][2], const Unit& u, int wr, int wc, int fr, int fq,
;                                               const EpiArgs& ea, const float (&rs_pre)[2][4]) {
;     ...
;   if constexpr (EPI == EPI_SWIGLU) {
; #pragma unroll
;     for (int ai = 0; ai < 2; ++ai)
; #pragma unroll
;       for (int m = 0; m < 4; ++m) {
;         const int row = row0 + ai * 128 + m * 16;
;         const float rs = rsr[ai][m];
;         u16* rowp = ea.out_bf + (size_t)row * 2816 + u.pn * 128 + wc * 32 + 8 * fq;
;         uint2 hp2[2];
; #pragma unroll
;         for (int n = 0; n < 2; ++n) {
;           f32x4 g = acc[ai][0][m][n] * rs, uu = acc[ai][1][m][n] * rs, h;
; #pragma unroll
;           for (int i = 0; i < 4; ++i) h[i] = g[i] * sigmoidf_(g[i]) * uu[i];
;           hp2[n] = pack4(h);
;         }
;         *reinterpret_cast<uint4*>(rowp) = make_uint4(hp2[0].x, hp2[0].y, hp2[1].x, hp2[1].y);
;       }
;     ...
;       if (!has_next) break;
; #pragma unroll
;       for (int a = 0; a < 2; ++a)
; #pragma unroll
;         for (int b = 0; b < 2; ++b)
; #pragma unroll
;           for (int m = 0; m < 4; ++m)
; #pragma unroll
;             for (int n = 0; n < 2; ++n) acc[a][b][m][n] = (f32x4){0.f, 0.f, 0.f, 0.f};
;       cur = nxt; cA = nA; cB = nB; ++ui;
;       G_PRELOAD_RS(cur);
	v_pk_mul_f32 v[174:175], v[36:37], v[170:171] op_sel_hi:[1,0]
	v_pk_mul_f32 v[176:177], v[38:39], v[170:171] op_sel_hi:[1,0]
	v_exp_f32_e32 v174, v174
	v_exp_f32_e32 v176, v176
	v_exp_f32_e32 v175, v175
	v_exp_f32_e32 v177, v177
	v_pk_mul_f32 v[32:33], v[36:37], v[32:33]
	v_pk_mul_f32 v[34:35], v[38:39], v[34:35]
	v_pk_add_f32 v[174:175], v[174:175], 1.0 op_sel_hi:[1,0]
	v_pk_add_f32 v[176:177], v[176:177], 1.0 op_sel_hi:[1,0]
	v_rcp_f32_e32 v174, v174
	v_rcp_f32_e32 v176, v176
	v_rcp_f32_e32 v175, v175
	v_rcp_f32_e32 v177, v177
	v_pk_mul_f32 v[174:175], v[174:175], v[172:173] op_sel_hi:[1,0]
	v_pk_mul_f32 v[176:177], v[176:177], v[172:173] op_sel_hi:[1,0]
	v_pk_mul_f32 v[36:37], v[32:33], v[174:175]
	v_pk_mul_f32 v[38:39], v[34:35], v[176:177]
	v_cvt_pk_bf16_f32 v44, v44, v45
	v_cvt_pk_bf16_f32 v45, v46, v47
	v_cvt_pk_bf16_f32 v46, v36, v37
	v_cvt_pk_bf16_f32 v47, v38, v39
	s_mul_i32 s37, s3, 144
	v_add_u32_e32 v161, s37, v160
	global_store_dwordx4 v161, v[44:47], s[42:43]
	v_mul_f32_e32 v170, 0xbfb8aa3b, v168
	v_mul_f32_e32 v172, v168, v168
	v_pk_mul_f32 v[174:175], v[28:29], v[170:171] op_sel_hi:[1,0]
	v_pk_mul_f32 v[176:177], v[30:31], v[170:171] op_sel_hi:[1,0]
	v_exp_f32_e32 v174, v174
	v_exp_f32_e32 v176, v176
	v_exp_f32_e32 v175, v175
	v_exp_f32_e32 v177, v177
	v_pk_mul_f32 v[24:25], v[28:29], v[24:25]
	v_pk_mul_f32 v[26:27], v[30:31], v[26:27]
	v_pk_add_f32 v[174:175], v[174:175], 1.0 op_sel_hi:[1,0]
	v_pk_add_f32 v[176:177], v[176:177], 1.0 op_sel_hi:[1,0]
	v_rcp_f32_e32 v174, v174
	v_rcp_f32_e32 v176, v176
	v_rcp_f32_e32 v175, v175
	v_rcp_f32_e32 v177, v177
	v_pk_mul_f32 v[174:175], v[174:175], v[172:173] op_sel_hi:[1,0]
	v_pk_mul_f32 v[176:177], v[176:177], v[172:173] op_sel_hi:[1,0]
	v_pk_mul_f32 v[28:29], v[24:25], v[174:175]
	v_pk_mul_f32 v[30:31], v[26:27], v[176:177]
	v_pk_mul_f32 v[174:175], v[20:21], v[170:171] op_sel_hi:[1,0]
	v_pk_mul_f32 v[176:177], v[22:23], v[170:171] op_sel_hi:[1,0]
	v_exp_f32_e32 v174, v174
	v_exp_f32_e32 v176, v176
	v_exp_f32_e32 v175, v175
	v_exp_f32_e32 v177, v177
	v_pk_mul_f32 v[16:17], v[20:21], v[16:17]
	v_pk_mul_f32 v[18:19], v[22:23], v[18:19]
	v_pk_add_f32 v[174:175], v[174:175], 1.0 op_sel_hi:[1,0]
	v_pk_add_f32 v[176:177], v[176:177], 1.0 op_sel_hi:[1,0]
	v_rcp_f32_e32 v174, v174
	v_rcp_f32_e32 v176, v176
	v_rcp_f32_e32 v175, v175
	v_rcp_f32_e32 v177, v177
	v_pk_mul_f32 v[174:175], v[174:175], v[172:173] op_sel_hi:[1,0]
	v_pk_mul_f32 v[176:177], v[176:177], v[172:173] op_sel_hi:[1,0]
	v_pk_mul_f32 v[20:21], v[16:17], v[174:175]
	v_pk_mul_f32 v[22:23], v[18:19], v[176:177]
	v_cvt_pk_bf16_f32 v28, v28, v29
	v_cvt_pk_bf16_f32 v29, v30, v31
	v_cvt_pk_bf16_f32 v30, v20, v21
	v_cvt_pk_bf16_f32 v31, v22, v23
	s_mul_i32 s37, s3, 160
	v_add_u32_e32 v161, s37, v160
	global_store_dwordx4 v161, v[28:31], s[42:43]
	v_mul_f32_e32 v170, 0xbfb8aa3b, v169
	v_mul_f32_e32 v172, v169, v169
	v_pk_mul_f32 v[174:175], v[12:13], v[170:171] op_sel_hi:[1,0]
	v_pk_mul_f32 v[176:177], v[14:15], v[170:171] op_sel_hi:[1,0]
	v_exp_f32_e32 v174, v174
	v_exp_f32_e32 v176, v176
	v_exp_f32_e32 v175, v175
	v_exp_f32_e32 v177, v177
	v_pk_mul_f32 v[8:9], v[12:13], v[8:9]
	v_pk_mul_f32 v[10:11], v[14:15], v[10:11]
	v_pk_add_f32 v[174:175], v[174:175], 1.0 op_sel_hi:[1,0]
	v_pk_add_f32 v[176:177], v[176:177], 1.0 op_sel_hi:[1,0]
	v_rcp_f32_e32 v174, v174
	v_rcp_f32_e32 v176, v176
	v_rcp_f32_e32 v175, v175
	v_rcp_f32_e32 v177, v177
	v_pk_mul_f32 v[174:175], v[174:175], v[172:173] op_sel_hi:[1,0]
	v_pk_mul_f32 v[176:177], v[176:177], v[172:173] op_sel_hi:[1,0]
	v_pk_mul_f32 v[12:13], v[8:9], v[174:175]
	v_pk_mul_f32 v[14:15], v[10:11], v[176:177]
	v_pk_mul_f32 v[174:175], v[4:5], v[170:171] op_sel_hi:[1,0]
	v_pk_mul_f32 v[176:177], v[6:7], v[170:171] op_sel_hi:[1,0]
	v_exp_f32_e32 v174, v174
	v_exp_f32_e32 v176, v176
	v_exp_f32_e32 v175, v175
	v_exp_f32_e32 v177, v177
	v_pk_mul_f32 v[0:1], v[4:5], v[0:1]
	v_pk_mul_f32 v[2:3], v[6:7], v[2:3]
	v_pk_add_f32 v[174:175], v[174:175], 1.0 op_sel_hi:[1,0]
	v_pk_add_f32 v[176:177], v[176:177], 1.0 op_sel_hi:[1,0]
	v_rcp_f32_e32 v174, v174
	v_rcp_f32_e32 v176, v176
	v_rcp_f32_e32 v175, v175
	v_rcp_f32_e32 v177, v177
	v_pk_mul_f32 v[174:175], v[174:175], v[172:173] op_sel_hi:[1,0]
	v_pk_mul_f32 v[176:177], v[176:177], v[172:173] op_sel_hi:[1,0]
	v_pk_mul_f32 v[4:5], v[0:1], v[174:175]
	v_pk_mul_f32 v[6:7], v[2:3], v[176:177]
	v_cvt_pk_bf16_f32 v12, v12, v13
	v_cvt_pk_bf16_f32 v13, v14, v15
	v_cvt_pk_bf16_f32 v14, v4, v5
	v_cvt_pk_bf16_f32 v15, v6, v7
	s_mul_i32 s37, s3, 176
	v_add_u32_e32 v161, s37, v160
	global_store_dwordx4 v161, v[12:15], s[42:43]
	s_and_b64 vcc, exec, s[0:1]
	s_mov_b64 s[36:37], -1
	s_cbranch_vccnz .LBB0_903
	v_lshl_add_u32 v0, s71, 8, v113
	v_ashrrev_i32_e32 v1, 31, v0
	v_lshl_add_u64 v[0:1], v[0:1], 2, s[4:5]
	global_load_dword v149, v[0:1], off
	global_load_dword v148, v[0:1], off offset:64
	global_load_dword v147, v[0:1], off offset:128
	global_load_dword v146, v[0:1], off offset:192
	global_load_dword v143, v[0:1], off offset:512
	global_load_dword v142, v[0:1], off offset:576
	global_load_dword v141, v[0:1], off offset:640
	global_load_dword v140, v[0:1], off offset:704
	s_mov_b64 s[36:37], 0
	s_branch .LBB0_903
